# LRH: LRU pass-A gates - sigmoid argument -L2E*(acc+e) as one v_fma_f32 (3 setup + 16 fma instead of 32 add/mul per chunk)
# speedup vs baseline: 1.0061x; 1.0061x over previous
; #define LAS __attribute__((address_space(3)))
; __device__ __forceinline__ float fast_sigmoid(float z) { return __builtin_amdgcn_rcpf(1.f + __builtin_amdgcn_exp2f(-z * L2E)); }
; __device__ __forceinline__ void lru_item(const Args& a, LAS unsigned char* lds, const int s, const int seg, const int hb, const int tid_in, const int lane_in, const int wave) {
;     ...
;         for (int mi = 0; mi < 2; ++mi) { const int mt = mt0 + mi; f32x4 pr = {0.f, 0.f, 0.f, 0.f}, pi = {0.f, 0.f, 0.f, 0.f};
; #pragma unroll
;             for (int ks = 0; ks < 2; ++ks) { const bf16x8 af = *(const LAS bf16x8*)(xcb + (mt * 16 + fr) * 72 + ks * 32 + fq * 8);
;                 pr = __builtin_amdgcn_mfma_f32_16x16x32_bf16(af, brg[ks], pr, 0, 0, 0); pi = __builtin_amdgcn_mfma_f32_16x16x32_bf16(af, big[ks], pi, 0, 0, 0); }
; #pragma unroll
;             for (int i = 0; i < 4; ++i) { const int t = mt * 16 + 4 * fq + i;
;                 const float r = fast_sigmoid(pr[i] + e_brg), ig = fast_sigmoid(pi[i] + e_big);
;                 const float av = __builtin_amdgcn_exp2f(r * e_ls);
;                 float mult = sqrtf(fmaxf(1.f - av * av, 0.f));
;                 if (!fin && tb + k * 64 + t == 0) mult = 1.f;
;                 const float xcv = xcf[t * 68 + jt * 16 + fr];
;                 LA[t * 64 + jt * 16 + fr] = av; LB[t * 64 + jt * 16 + fr] = mult * ig * xcv; } }
.LBB0_565:
	ds_read_b128 v[86:89], v120
	ds_read_b128 v[90:93], v120 offset:64
	ds_read_b128 v[160:163], v122
	ds_read_b128 v[164:167], v122 offset:64
	ds_read_b32 v172, v121 offset:9216
	ds_read_b32 v173, v121 offset:9488
	ds_read_b32 v174, v121 offset:9760
	ds_read_b32 v175, v121 offset:10032
	ds_read_b32 v176, v123 offset:9216
	ds_read_b32 v177, v123 offset:9488
	ds_read_b32 v178, v123 offset:9760
	ds_read_b32 v179, v123 offset:10032
	s_waitcnt lgkmcnt(11)
	v_mfma_f32_16x16x32_bf16 v[94:97], v[86:89], v[44:47], 0
	s_waitcnt lgkmcnt(9)
	v_mfma_f32_16x16x32_bf16 v[168:171], v[160:163], v[44:47], 0
	v_mfma_f32_16x16x32_bf16 v[94:97], v[90:93], v[52:55], v[94:97]
	s_waitcnt lgkmcnt(8)
	v_mfma_f32_16x16x32_bf16 v[168:171], v[164:167], v[52:55], v[168:171]
	v_mfma_f32_16x16x32_bf16 v[86:89], v[86:89], v[48:51], 0
	v_mfma_f32_16x16x32_bf16 v[160:163], v[160:163], v[48:51], 0
	v_mfma_f32_16x16x32_bf16 v[86:89], v[90:93], v[56:59], v[86:89]
	v_mfma_f32_16x16x32_bf16 v[160:163], v[164:167], v[56:59], v[160:163]
	s_nop 7
	v_mov_b32_e32 v192, 0xbfb8aa3b
	v_mul_f32_e32 v193, 0xbfb8aa3b, v102
	v_mul_f32_e32 v143, 0xbfb8aa3b, v103
	v_fma_f32 v94, v94, v192, v193
	v_fma_f32 v95, v95, v192, v193
	v_fma_f32 v96, v96, v192, v193
	v_fma_f32 v97, v97, v192, v193
	v_exp_f32_e32 v94, v94
	v_exp_f32_e32 v95, v95
	v_exp_f32_e32 v96, v96
	v_exp_f32_e32 v97, v97
	v_fma_f32 v86, v86, v192, v143
	v_fma_f32 v87, v87, v192, v143
	v_fma_f32 v88, v88, v192, v143
	v_fma_f32 v89, v89, v192, v143
	v_add_f32_e32 v94, 1.0, v94
	v_add_f32_e32 v95, 1.0, v95
	v_add_f32_e32 v96, 1.0, v96
	v_add_f32_e32 v97, 1.0, v97
	v_rcp_f32_e32 v94, v94
	v_rcp_f32_e32 v95, v95
	v_rcp_f32_e32 v96, v96
	v_rcp_f32_e32 v97, v97
	v_exp_f32_e32 v86, v86
	v_exp_f32_e32 v87, v87
	v_exp_f32_e32 v88, v88
	v_exp_f32_e32 v89, v89
	v_mul_f32_e32 v94, v105, v94
	v_mul_f32_e32 v95, v105, v95
	v_mul_f32_e32 v96, v105, v96
	v_mul_f32_e32 v97, v105, v97
	v_exp_f32_e32 v94, v94
	v_exp_f32_e32 v95, v95
	v_exp_f32_e32 v96, v96
	v_exp_f32_e32 v97, v97
	v_add_f32_e32 v86, 1.0, v86
	v_add_f32_e32 v87, 1.0, v87
	v_add_f32_e32 v88, 1.0, v88
	v_add_f32_e32 v89, 1.0, v89
	v_rcp_f32_e32 v86, v86
	v_rcp_f32_e32 v87, v87
	v_rcp_f32_e32 v88, v88
	v_rcp_f32_e32 v89, v89
	v_fma_f32 v180, -v94, v94, 1.0
	v_fma_f32 v181, -v95, v95, 1.0
	v_fma_f32 v182, -v96, v96, 1.0
	v_fma_f32 v183, -v97, v97, 1.0
	v_max_f32_e32 v180, 0, v180
	v_max_f32_e32 v181, 0, v181
	v_max_f32_e32 v182, 0, v182
	v_max_f32_e32 v183, 0, v183
	v_sqrt_f32_e32 v184, v180
	v_sqrt_f32_e32 v185, v181
	v_sqrt_f32_e32 v186, v182
	v_sqrt_f32_e32 v187, v183
	v_add_u32_e32 v188, -1, v184
	v_add_u32_e32 v189, -1, v185
	v_add_u32_e32 v190, -1, v186
	v_add_u32_e32 v191, -1, v187
	v_add_u32_e32 v98, 1, v184
	v_add_u32_e32 v99, 1, v185
	v_add_u32_e32 v100, 1, v186
	v_add_u32_e32 v101, 1, v187
	v_fma_f32 v1, -v188, v184, v180
	v_fma_f32 v2, -v189, v185, v181
	v_fma_f32 v3, -v190, v186, v182
	v_fma_f32 v126, -v191, v187, v183
	v_fma_f32 v180, -v98, v184, v180
	v_fma_f32 v181, -v99, v185, v181
	v_fma_f32 v182, -v100, v186, v182
	v_fma_f32 v183, -v101, v187, v183
	v_cmp_ge_f32_e64 vcc, 0, v1
	v_cmp_ge_f32_e64 s[0:1], 0, v2
	v_cmp_ge_f32_e64 s[82:83], 0, v3
	v_cndmask_b32_e64 v184, v184, v188, vcc
	v_cmp_ge_f32_e64 vcc, 0, v126
	v_cndmask_b32_e64 v185, v185, v189, s[0:1]
	v_cndmask_b32_e64 v186, v186, v190, s[82:83]
	v_cndmask_b32_e64 v187, v187, v191, vcc
	v_cmp_lt_f32_e64 s[0:1], 0, v180
	v_cmp_lt_f32_e64 s[82:83], 0, v181
	v_cmp_lt_f32_e64 vcc, 0, v182
	v_cndmask_b32_e64 v184, v184, v98, s[0:1]
	v_cmp_lt_f32_e64 s[0:1], 0, v183
	v_cndmask_b32_e64 v185, v185, v99, s[82:83]
	v_cndmask_b32_e64 v186, v186, v100, vcc
	v_cmp_ne_u32_e32 vcc, v116, v104
	v_cndmask_b32_e64 v187, v187, v101, s[0:1]
	v_mul_f32_e32 v87, v87, v185
	v_mul_f32_e32 v88, v88, v186
	v_cndmask_b32_e32 v184, 1.0, v184, vcc
	v_mul_f32_e32 v89, v89, v187
	s_waitcnt lgkmcnt(4)
	v_mul_f32_e32 v86, v86, v184
	v_mul_f32_e32 v87, v173, v87
	v_mul_f32_e32 v88, v174, v88
	v_mul_f32_e32 v89, v175, v89
	v_mul_f32_e32 v86, v172, v86
	ds_write2st64_b32 v108, v95, v87 offset0:104 offset1:168
	ds_write2st64_b32 v109, v96, v88 offset0:104 offset1:168
	ds_write2st64_b32 v110, v97, v89 offset0:104 offset1:168
	ds_write2st64_b32 v107, v94, v86 offset0:104 offset1:168
	v_fma_f32 v168, v168, v192, v193
	v_fma_f32 v169, v169, v192, v193
	v_fma_f32 v170, v170, v192, v193
	v_fma_f32 v171, v171, v192, v193
	v_exp_f32_e32 v168, v168
	v_exp_f32_e32 v169, v169
	v_exp_f32_e32 v170, v170
	v_exp_f32_e32 v171, v171
	v_fma_f32 v160, v160, v192, v143
	v_fma_f32 v161, v161, v192, v143
	v_fma_f32 v162, v162, v192, v143
	v_fma_f32 v163, v163, v192, v143
	v_add_f32_e32 v168, 1.0, v168
	v_add_f32_e32 v169, 1.0, v169
	v_add_f32_e32 v170, 1.0, v170
	v_add_f32_e32 v171, 1.0, v171
	v_rcp_f32_e32 v168, v168
	v_rcp_f32_e32 v169, v169
	v_rcp_f32_e32 v170, v170
	v_rcp_f32_e32 v171, v171
	v_exp_f32_e32 v160, v160
	v_exp_f32_e32 v161, v161
	v_exp_f32_e32 v162, v162
	v_exp_f32_e32 v163, v163
	v_mul_f32_e32 v168, v105, v168
	v_mul_f32_e32 v169, v105, v169
	v_mul_f32_e32 v170, v105, v170
	v_mul_f32_e32 v171, v105, v171
	v_exp_f32_e32 v168, v168
	v_exp_f32_e32 v169, v169
	v_exp_f32_e32 v170, v170
	v_exp_f32_e32 v171, v171
	v_add_f32_e32 v160, 1.0, v160
	v_add_f32_e32 v161, 1.0, v161
	v_add_f32_e32 v162, 1.0, v162
	v_add_f32_e32 v163, 1.0, v163
	v_rcp_f32_e32 v160, v160
	v_rcp_f32_e32 v161, v161
	v_rcp_f32_e32 v162, v162
	v_rcp_f32_e32 v163, v163
	v_fma_f32 v180, -v168, v168, 1.0
	v_fma_f32 v181, -v169, v169, 1.0
	v_fma_f32 v182, -v170, v170, 1.0
	v_fma_f32 v183, -v171, v171, 1.0
	v_max_f32_e32 v180, 0, v180
	v_max_f32_e32 v181, 0, v181
	v_max_f32_e32 v182, 0, v182
; __device__ __forceinline__ float fast_sigmoid(float z) { return __builtin_amdgcn_rcpf(1.f + __builtin_amdgcn_exp2f(-z * L2E)); }
; __device__ __forceinline__ void lru_item(const Args& a, LAS unsigned char* lds, const int s, const int seg, const int hb, const int tid_in, const int lane_in, const int wave) {
;     ...
;             for (int i = 0; i < 4; ++i) { const int t = mt * 16 + 4 * fq + i;
;                 const float r = fast_sigmoid(pr[i] + e_brg), ig = fast_sigmoid(pi[i] + e_big);
;                 const float av = __builtin_amdgcn_exp2f(r * e_ls);
;                 float mult = sqrtf(fmaxf(1.f - av * av, 0.f));
;                 if (!fin && tb + k * 64 + t == 0) mult = 1.f;
;                 const float xcv = xcf[t * 68 + jt * 16 + fr];
;                 LA[t * 64 + jt * 16 + fr] = av; LB[t * 64 + jt * 16 + fr] = mult * ig * xcv; } }
;         __syncthreads();
;         float av[8], bv[8];
;         { float Ap = 1.f, Bp = 0.f;
; #pragma unroll
;           for (int i = 0; i < 8; ++i) { av[i] = LA[(sseg * 8 + i) * 64 + sj]; bv[i] = LB[(sseg * 8 + i) * 64 + sj]; Bp = av[i] * Bp + bv[i]; Ap *= av[i]; }
;           SA[sseg * 64 + sj] = Ap; SB[sseg * 64 + sj] = Bp; }
;         __syncthreads();
	v_max_f32_e32 v183, 0, v183
	v_sqrt_f32_e32 v184, v180
	v_sqrt_f32_e32 v185, v181
	v_sqrt_f32_e32 v186, v182
	v_sqrt_f32_e32 v187, v183
	v_add_u32_e32 v188, -1, v184
	v_add_u32_e32 v189, -1, v185
	v_add_u32_e32 v190, -1, v186
	v_add_u32_e32 v191, -1, v187
	v_add_u32_e32 v98, 1, v184
	v_add_u32_e32 v99, 1, v185
	v_add_u32_e32 v100, 1, v186
	v_add_u32_e32 v101, 1, v187
	v_fma_f32 v1, -v188, v184, v180
	v_fma_f32 v2, -v189, v185, v181
	v_fma_f32 v3, -v190, v186, v182
	v_fma_f32 v126, -v191, v187, v183
	v_fma_f32 v180, -v98, v184, v180
	v_fma_f32 v181, -v99, v185, v181
	v_fma_f32 v182, -v100, v186, v182
	v_fma_f32 v183, -v101, v187, v183
	v_cmp_ge_f32_e64 vcc, 0, v1
	v_cmp_ge_f32_e64 s[0:1], 0, v2
	v_cmp_ge_f32_e64 s[82:83], 0, v3
	v_cndmask_b32_e64 v184, v184, v188, vcc
	v_cmp_ge_f32_e64 vcc, 0, v126
	v_cndmask_b32_e64 v185, v185, v189, s[0:1]
	v_cndmask_b32_e64 v186, v186, v190, s[82:83]
	v_cndmask_b32_e64 v187, v187, v191, vcc
	v_cmp_lt_f32_e64 s[0:1], 0, v180
	v_cmp_lt_f32_e64 s[82:83], 0, v181
	v_cmp_lt_f32_e64 vcc, 0, v182
	v_cndmask_b32_e64 v184, v184, v98, s[0:1]
	v_cmp_lt_f32_e64 s[0:1], 0, v183
	v_cndmask_b32_e64 v185, v185, v99, s[82:83]
	v_cndmask_b32_e64 v186, v186, v100, vcc
	v_cmp_ne_u32_e32 vcc, v117, v104
	v_cndmask_b32_e64 v187, v187, v101, s[0:1]
	v_mul_f32_e32 v161, v161, v185
	v_mul_f32_e32 v162, v162, v186
	v_cndmask_b32_e32 v184, 1.0, v184, vcc
	v_mul_f32_e32 v163, v163, v187
	s_waitcnt lgkmcnt(0)
	v_mul_f32_e32 v160, v160, v184
	v_mul_f32_e32 v161, v177, v161
	v_mul_f32_e32 v162, v178, v162
	v_mul_f32_e32 v163, v179, v163
	v_mul_f32_e32 v160, v176, v160
	ds_write2st64_b32 v112, v169, v161 offset0:104 offset1:168
	ds_write2st64_b32 v113, v170, v162 offset0:104 offset1:168
	ds_write2st64_b32 v114, v171, v163 offset0:104 offset1:168
	ds_write2st64_b32 v111, v168, v160 offset0:104 offset1:168
	s_waitcnt lgkmcnt(0)
	s_barrier
	ds_read2st64_b32 v[96:97], v124 offset0:168 offset1:169
	ds_read2st64_b32 v[98:99], v124 offset0:104 offset1:105
	ds_read2st64_b32 v[92:93], v124 offset0:106 offset1:107
	ds_read2st64_b32 v[88:89], v124 offset0:108 offset1:109
	ds_read2st64_b32 v[86:87], v124 offset0:110 offset1:111
	ds_read2st64_b32 v[94:95], v124 offset0:170 offset1:171
	ds_read2st64_b32 v[90:91], v124 offset0:172 offset1:173
	ds_read2st64_b32 v[2:3], v124 offset0:174 offset1:175
	s_waitcnt lgkmcnt(6)
	v_fma_f32 v1, 0, v98, v96
	v_fma_f32 v1, v1, v99, v97
	v_mul_f32_e32 v100, v98, v99
	s_waitcnt lgkmcnt(2)
	v_fma_f32 v1, v1, v92, v94
	v_mul_f32_e32 v100, v100, v92
	v_fma_f32 v1, v1, v93, v95
	v_mul_f32_e32 v100, v100, v93
	s_waitcnt lgkmcnt(1)
	v_fma_f32 v1, v1, v88, v90
	v_mul_f32_e32 v100, v100, v88
	v_fma_f32 v1, v1, v89, v91
	v_mul_f32_e32 v100, v100, v89
	s_waitcnt lgkmcnt(0)
	v_fma_f32 v1, v1, v86, v2
	v_mul_f32_e32 v100, v100, v86
	v_fma_f32 v1, v1, v87, v3
	v_mul_f32_e32 v100, v100, v87
	ds_write2st64_b32 v125, v100, v1 offset0:232 offset1:240
	v_and_or_b32 v1, v104, 64, v77
	v_lshl_add_u32 v1, v1, 2, 0
	s_waitcnt lgkmcnt(0)
	s_barrier
; __device__ __forceinline__ unsigned cvt_pk_bf16(float lo, float hi) { unsigned r; asm volatile("v_cvt_pk_bf16_f32 %0, %1, %2" : "=v"(r) : "v"(lo), "v"(hi)); return r; }
; __device__ __forceinline__ void lru_item(const Args& a, LAS unsigned char* lds, const int s, const int seg, const int hb, const int tid_in, const int lane_in, const int wave) {
;     ...
;         { float hv = HC[(k & 1) * 64 + sj], pv = PC[(k & 1) * 64 + sj];
; #pragma unroll
;           for (int q = 0; q < 8; ++q) { const float A_ = SA[q * 64 + sj], B_ = SB[q * 64 + sj]; if (q < sseg) { hv = A_ * hv + B_; pv *= A_; } }
;           const size_t ob = (size_t)(row0 + tb + k * 64 + sseg * 8) * D + c0 + sj;
; #pragma unroll
;           for (int i = 0; i < 8; ++i) { hv = av[i] * hv + bv[i]; pv *= av[i];
;               if (fin) { const float g = __uint_as_float((unsigned)gcur[i] << 16); YL[(size_t)(row0 + tb + k * 64 + sseg * 8 + i) * (2 * D) + c0 + sj] = (bf16_t)(cvt_pk_bf16(hv * g, 0.f) & 0xffffu); }
;               else { const unsigned w = cvt_pk_bf16(hv, pv); HL[ob + (size_t)i * D] = (bf16_t)(w & 0xffffu); PB[ob + (size_t)i * D] = (bf16_t)(w >> 16); } }
;           if (sseg == 7) { HC[((k + 1) & 1) * 64 + sj] = hv; PC[((k + 1) & 1) * 64 + sj] = pv;
;               if (k + 1 == nch) { if (fin) a.out[O_HS + (size_t)(s - 1) * D + c0 + sj] = hv;
;                   else { float* ag = (float*)(ws + WS_AGG) + (size_t)seg * 2048 + c0 + sj; ag[0] = pv; ag[1024] = hv; } } } }
	ds_read2st64_b32 v[100:101], v1 offset0:248 offset1:250
	ds_read2st64_b32 v[160:161], v106 offset0:232 offset1:240
	ds_read2st64_b32 v[162:163], v106 offset0:233 offset1:241
	ds_read2st64_b32 v[164:165], v106 offset0:234 offset1:242
	ds_read2st64_b32 v[166:167], v106 offset0:235 offset1:243
	ds_read2st64_b32 v[168:169], v106 offset0:236 offset1:244
	ds_read2st64_b32 v[170:171], v106 offset0:237 offset1:245
	ds_read2st64_b32 v[172:173], v106 offset0:238 offset1:246
	ds_read2st64_b32 v[174:175], v106 offset0:239 offset1:247
	s_mov_b64 s[0:1], exec
	s_waitcnt lgkmcnt(0)
	s_and_b64 exec, s[0:1], s[4:5]
	v_fma_f32 v100, v100, v160, v161
	v_mul_f32_e32 v101, v101, v160
	s_and_b64 exec, s[0:1], s[6:7]
	v_fma_f32 v100, v100, v162, v163
	v_mul_f32_e32 v101, v101, v162
	s_and_b64 exec, s[0:1], s[8:9]
	v_fma_f32 v100, v100, v164, v165
	v_mul_f32_e32 v101, v101, v164
	s_and_b64 exec, s[0:1], s[10:11]
	v_fma_f32 v100, v100, v166, v167
	v_mul_f32_e32 v101, v101, v166
	s_and_b64 exec, s[0:1], s[12:13]
	v_fma_f32 v100, v100, v168, v169
	v_mul_f32_e32 v101, v101, v168
	s_and_b64 exec, s[0:1], s[14:15]
	v_fma_f32 v100, v100, v170, v171
	v_mul_f32_e32 v101, v101, v170
	s_and_b64 exec, s[0:1], s[16:17]
	v_fma_f32 v100, v100, v172, v173
	v_mul_f32_e32 v101, v101, v172
	s_and_b64 exec, s[0:1], s[18:19]
	v_fma_f32 v100, v100, v174, v175
	v_mul_f32_e32 v101, v101, v174
	s_mov_b64 exec, s[0:1]
	v_add_u32_e32 v128, v115, v104
	v_ashrrev_i32_e32 v129, 31, v128
	s_waitcnt lgkmcnt(0)
	v_fma_f32 v1, v98, v100, v96
	v_mul_f32_e32 v96, v98, v101
	v_lshlrev_b64 v[100:101], 11, v[128:129]
	v_lshl_or_b32 v100, v84, 1, v100
	v_lshl_add_u64 v[128:129], s[26:27], 0, v[100:101]
	v_lshl_add_u64 v[100:101], s[28:29], 0, v[100:101]
	v_cvt_pk_bf16_f32 v98, v1, v96
	global_store_short v[128:129], v98, off
	global_store_short_d16_hi v[100:101], v98, off
	v_fmac_f32_e32 v97, v99, v1
	v_mul_f32_e32 v1, v99, v96
	v_cvt_pk_bf16_f32 v96, v97, v1
	global_store_short v[128:129], v96, off offset:2048
	global_store_short_d16_hi v[100:101], v96, off offset:2048
	v_add_co_u32_e32 v96, vcc, s94, v128
	v_fma_f32 v94, v92, v97, v94
	s_nop 0
	v_addc_co_u32_e32 v97, vcc, 0, v129, vcc
	v_add_co_u32_e32 v98, vcc, s95, v128
	v_mul_f32_e32 v1, v92, v1
	s_nop 0
	v_addc_co_u32_e32 v99, vcc, 0, v129, vcc
	v_add_co_u32_e32 v140, vcc, s94, v100
	v_cvt_pk_bf16_f32 v92, v94, v1
	global_store_short v[98:99], v92, off offset:-4096
	s_nop 0
	v_addc_co_u32_e32 v141, vcc, 0, v101, vcc
	v_add_co_u32_e32 v142, vcc, s95, v100
	v_fmac_f32_e32 v95, v93, v94
	s_nop 0
	v_addc_co_u32_e32 v143, vcc, 0, v101, vcc
	global_store_short_d16_hi v[142:143], v92, off offset:-4096
	v_mul_f32_e32 v1, v93, v1
	v_cvt_pk_bf16_f32 v92, v95, v1
	global_store_short v[96:97], v92, off offset:2048
	global_store_short_d16_hi v[140:141], v92, off offset:2048
	v_fma_f32 v90, v88, v95, v90
	v_mul_f32_e32 v1, v88, v1
	v_cvt_pk_bf16_f32 v88, v90, v1
	global_store_short v[98:99], v88, off
	global_store_short_d16_hi v[142:143], v88, off
	v_fmac_f32_e32 v91, v89, v90
	v_mul_f32_e32 v1, v89, v1
	v_cvt_pk_bf16_f32 v88, v91, v1
	s_movk_i32 s0, 0x3000
	global_store_short v[98:99], v88, off offset:2048
	global_store_short_d16_hi v[142:143], v88, off offset:2048
	v_add_co_u32_e32 v88, vcc, s0, v128
	v_fma_f32 v2, v86, v91, v2
	s_nop 0
	v_addc_co_u32_e32 v89, vcc, 0, v129, vcc
	v_add_co_u32_e32 v90, vcc, 0x3000, v100
	v_mul_f32_e32 v1, v86, v1
	s_nop 0
	v_addc_co_u32_e32 v91, vcc, 0, v101, vcc
	v_cvt_pk_bf16_f32 v86, v2, v1
	global_store_short v[88:89], v86, off
	global_store_short_d16_hi v[90:91], v86, off
	v_fmac_f32_e32 v3, v87, v2
	v_mul_f32_e32 v2, v87, v1
	v_cvt_pk_bf16_f32 v1, v3, v2
	s_mov_b64 s[96:97], -1
	s_mov_b64 s[0:1], 0
	global_store_short v[88:89], v1, off offset:2048
	global_store_short_d16_hi v[90:91], v1, off offset:2048
	s_and_saveexec_b64 vcc, s[2:3]
	s_cbranch_execz .LBB0_586
	v_add_u32_e32 v1, 64, v104
	v_and_b32_e32 v86, 64, v1
	v_lshl_add_u32 v86, v86, 2, v106
	s_cmp_eq_u32 s49, 15
	ds_write2st64_b32 v86, v3, v2 offset0:248 offset1:250
	s_cbranch_scc0 .LBB0_584
	global_store_dword v[80:81], v2, off
	global_store_dword v[82:83], v3, off
	s_branch .LBB0_585
